# grid barrier: drop the per-XCD generation republish atomic nobody waits on any more
# speedup vs baseline: 1.0145x; 1.0017x over previous
; __device__ __forceinline__ unsigned xb_ld(unsigned* p)              { return __hip_atomic_load(p, __ATOMIC_RELAXED, __HIP_MEMORY_SCOPE_AGENT); }
; __device__ __forceinline__ unsigned xb_add(unsigned* p, unsigned v) { return __hip_atomic_fetch_add(p, v, __ATOMIC_RELAXED, __HIP_MEMORY_SCOPE_AGENT); }
; #define XB_SPIN(cond, bar) do { unsigned _sp = 0; while (cond) { __builtin_amdgcn_s_sleep(1); \
;     if ((++_sp & 255u) == 0u) { if (xb_ld(&(bar)[XB_TMO])) break; if (_sp > XB_SPIN_CAP) { atomicAdd(&(bar)[XB_TMO], 1u); break; } } } } while (0)
; __device__ __forceinline__ void xcd_barrier(const XcdBarrier& b) {
;     ...
;             const unsigned og = xb_add(&bar[XB_TOP], 1u);
;             const unsigned tg = og / nx;
;             if (og + 1u == (tg + 1u) * nx) xb_add(&bar[XB_TOPGEN], 1u);
;             else XB_SPIN(xb_ld(&bar[XB_TOPGEN]) == tg, bar);
;             __builtin_amdgcn_fence(__ATOMIC_ACQUIRE, "agent");
;             xb_add(&bar[XB_XGEN(b.x)], 1u);
;             asm volatile("s_waitcnt vmcnt(0)" ::: "memory");
.LBB0_140:
	s_or_b64 exec, exec, s[6:7]
	s_mov_b64 s[6:7], exec
	v_mbcnt_lo_u32_b32 v2, s6, 0
	v_mbcnt_hi_u32_b32 v2, s7, v2
	v_cmp_eq_u32_e32 vcc, 0, v2
	s_waitcnt vmcnt(0)
	buffer_inv sc1
	s_and_saveexec_b64 s[8:9], vcc
	s_cbranch_execz .LBB0_142
	s_bcnt1_i32_b64 s3, s[6:7]
	v_mov_b32_e32 v2, 0x2000
	v_mov_b32_e32 v3, s3
.LBB0_142:
	s_or_b64 exec, exec, s[8:9]
	s_waitcnt vmcnt(0)

; __device__ __forceinline__ unsigned xb_ld(unsigned* p)              { return __hip_atomic_load(p, __ATOMIC_RELAXED, __HIP_MEMORY_SCOPE_AGENT); }
; __device__ __forceinline__ unsigned xb_add(unsigned* p, unsigned v) { return __hip_atomic_fetch_add(p, v, __ATOMIC_RELAXED, __HIP_MEMORY_SCOPE_AGENT); }
; #define XB_SPIN(cond, bar) do { unsigned _sp = 0; while (cond) { __builtin_amdgcn_s_sleep(1); \
;     if ((++_sp & 255u) == 0u) { if (xb_ld(&(bar)[XB_TMO])) break; if (_sp > XB_SPIN_CAP) { atomicAdd(&(bar)[XB_TMO], 1u); break; } } } } while (0)
; __device__ __forceinline__ void xcd_barrier(const XcdBarrier& b) {
;     ...
;             const unsigned og = xb_add(&bar[XB_TOP], 1u);
;             const unsigned tg = og / nx;
;             if (og + 1u == (tg + 1u) * nx) xb_add(&bar[XB_TOPGEN], 1u);
;             else XB_SPIN(xb_ld(&bar[XB_TOPGEN]) == tg, bar);
;             __builtin_amdgcn_fence(__ATOMIC_ACQUIRE, "agent");
;             xb_add(&bar[XB_XGEN(b.x)], 1u);
;             asm volatile("s_waitcnt vmcnt(0)" ::: "memory");
.LBB0_583:
	s_or_b64 exec, exec, s[8:9]
	s_mov_b64 s[8:9], exec
	v_mbcnt_lo_u32_b32 v2, s8, 0
	v_mbcnt_hi_u32_b32 v2, s9, v2
	v_cmp_eq_u32_e32 vcc, 0, v2
	s_waitcnt vmcnt(0)
	buffer_inv sc1
	s_and_saveexec_b64 s[10:11], vcc
	s_cbranch_execz .LBB0_585
	s_bcnt1_i32_b64 s8, s[8:9]
	v_mov_b32_e32 v2, 0x2000
	v_mov_b32_e32 v3, s8
.LBB0_585:
	s_or_b64 exec, exec, s[10:11]
	s_waitcnt vmcnt(0)

; __device__ __forceinline__ unsigned xb_ld(unsigned* p)              { return __hip_atomic_load(p, __ATOMIC_RELAXED, __HIP_MEMORY_SCOPE_AGENT); }
; __device__ __forceinline__ unsigned xb_add(unsigned* p, unsigned v) { return __hip_atomic_fetch_add(p, v, __ATOMIC_RELAXED, __HIP_MEMORY_SCOPE_AGENT); }
; #define XB_SPIN(cond, bar) do { unsigned _sp = 0; while (cond) { __builtin_amdgcn_s_sleep(1); \
;     if ((++_sp & 255u) == 0u) { if (xb_ld(&(bar)[XB_TMO])) break; if (_sp > XB_SPIN_CAP) { atomicAdd(&(bar)[XB_TMO], 1u); break; } } } } while (0)
; __device__ __forceinline__ void xcd_barrier(const XcdBarrier& b) {
;     ...
;             const unsigned og = xb_add(&bar[XB_TOP], 1u);
;             const unsigned tg = og / nx;
;             if (og + 1u == (tg + 1u) * nx) xb_add(&bar[XB_TOPGEN], 1u);
;             else XB_SPIN(xb_ld(&bar[XB_TOPGEN]) == tg, bar);
;             __builtin_amdgcn_fence(__ATOMIC_ACQUIRE, "agent");
;             xb_add(&bar[XB_XGEN(b.x)], 1u);
;             asm volatile("s_waitcnt vmcnt(0)" ::: "memory");
.LBB0_689:
	s_or_b64 exec, exec, s[10:11]
	s_mov_b64 s[10:11], exec
	v_mbcnt_lo_u32_b32 v2, s10, 0
	v_mbcnt_hi_u32_b32 v2, s11, v2
	v_cmp_eq_u32_e32 vcc, 0, v2
	s_waitcnt vmcnt(0)
	buffer_inv sc1
	s_and_saveexec_b64 s[12:13], vcc
	s_cbranch_execz .LBB0_691
	s_bcnt1_i32_b64 s10, s[10:11]
	v_mov_b32_e32 v2, 0x2000
	v_mov_b32_e32 v3, s10
.LBB0_691:
	s_or_b64 exec, exec, s[12:13]
	s_waitcnt vmcnt(0)

; __device__ __forceinline__ unsigned xb_ld(unsigned* p)              { return __hip_atomic_load(p, __ATOMIC_RELAXED, __HIP_MEMORY_SCOPE_AGENT); }
; __device__ __forceinline__ unsigned xb_add(unsigned* p, unsigned v) { return __hip_atomic_fetch_add(p, v, __ATOMIC_RELAXED, __HIP_MEMORY_SCOPE_AGENT); }
; #define XB_SPIN(cond, bar) do { unsigned _sp = 0; while (cond) { __builtin_amdgcn_s_sleep(1); \
;     if ((++_sp & 255u) == 0u) { if (xb_ld(&(bar)[XB_TMO])) break; if (_sp > XB_SPIN_CAP) { atomicAdd(&(bar)[XB_TMO], 1u); break; } } } } while (0)
; __device__ __forceinline__ void xcd_barrier(const XcdBarrier& b) {
;     ...
;             const unsigned og = xb_add(&bar[XB_TOP], 1u);
;             const unsigned tg = og / nx;
;             if (og + 1u == (tg + 1u) * nx) xb_add(&bar[XB_TOPGEN], 1u);
;             else XB_SPIN(xb_ld(&bar[XB_TOPGEN]) == tg, bar);
;             __builtin_amdgcn_fence(__ATOMIC_ACQUIRE, "agent");
;             xb_add(&bar[XB_XGEN(b.x)], 1u);
;             asm volatile("s_waitcnt vmcnt(0)" ::: "memory");
.LBB0_1002:
	s_or_b64 exec, exec, s[8:9]
	s_mov_b64 s[8:9], exec
	v_mbcnt_lo_u32_b32 v2, s8, 0
	v_mbcnt_hi_u32_b32 v2, s9, v2
	v_cmp_eq_u32_e32 vcc, 0, v2
	s_waitcnt vmcnt(0)
	buffer_inv sc1
	s_and_saveexec_b64 s[10:11], vcc
	s_cbranch_execz .LBB0_1004
	s_bcnt1_i32_b64 s3, s[8:9]
	v_mov_b32_e32 v2, 0x2000
	v_mov_b32_e32 v3, s3
.LBB0_1004:
	s_or_b64 exec, exec, s[10:11]
	s_waitcnt vmcnt(0)

; __device__ __forceinline__ unsigned xb_ld(unsigned* p)              { return __hip_atomic_load(p, __ATOMIC_RELAXED, __HIP_MEMORY_SCOPE_AGENT); }
; __device__ __forceinline__ unsigned xb_add(unsigned* p, unsigned v) { return __hip_atomic_fetch_add(p, v, __ATOMIC_RELAXED, __HIP_MEMORY_SCOPE_AGENT); }
; #define XB_SPIN(cond, bar) do { unsigned _sp = 0; while (cond) { __builtin_amdgcn_s_sleep(1); \
;     if ((++_sp & 255u) == 0u) { if (xb_ld(&(bar)[XB_TMO])) break; if (_sp > XB_SPIN_CAP) { atomicAdd(&(bar)[XB_TMO], 1u); break; } } } } while (0)
; __device__ __forceinline__ void xcd_barrier(const XcdBarrier& b) {
;     ...
;             const unsigned og = xb_add(&bar[XB_TOP], 1u);
;             const unsigned tg = og / nx;
;             if (og + 1u == (tg + 1u) * nx) xb_add(&bar[XB_TOPGEN], 1u);
;             else XB_SPIN(xb_ld(&bar[XB_TOPGEN]) == tg, bar);
;             __builtin_amdgcn_fence(__ATOMIC_ACQUIRE, "agent");
;             xb_add(&bar[XB_XGEN(b.x)], 1u);
;             asm volatile("s_waitcnt vmcnt(0)" ::: "memory");
.LBB0_1072:
	s_or_b64 exec, exec, s[8:9]
	s_mov_b64 s[8:9], exec
	v_mbcnt_lo_u32_b32 v2, s8, 0
	v_mbcnt_hi_u32_b32 v2, s9, v2
	v_cmp_eq_u32_e32 vcc, 0, v2
	s_waitcnt vmcnt(0)
	buffer_inv sc1
	s_and_saveexec_b64 s[10:11], vcc
	s_cbranch_execz .LBB0_1074
	s_bcnt1_i32_b64 s3, s[8:9]
	v_mov_b32_e32 v2, 0x2000
	v_mov_b32_e32 v3, s3
.LBB0_1074:
	s_or_b64 exec, exec, s[10:11]
	s_waitcnt vmcnt(0)

; __device__ __forceinline__ unsigned xb_ld(unsigned* p)              { return __hip_atomic_load(p, __ATOMIC_RELAXED, __HIP_MEMORY_SCOPE_AGENT); }
; __device__ __forceinline__ unsigned xb_add(unsigned* p, unsigned v) { return __hip_atomic_fetch_add(p, v, __ATOMIC_RELAXED, __HIP_MEMORY_SCOPE_AGENT); }
; #define XB_SPIN(cond, bar) do { unsigned _sp = 0; while (cond) { __builtin_amdgcn_s_sleep(1); \
;     if ((++_sp & 255u) == 0u) { if (xb_ld(&(bar)[XB_TMO])) break; if (_sp > XB_SPIN_CAP) { atomicAdd(&(bar)[XB_TMO], 1u); break; } } } } while (0)
; __device__ __forceinline__ void xcd_barrier(const XcdBarrier& b) {
;     ...
;             const unsigned og = xb_add(&bar[XB_TOP], 1u);
;             const unsigned tg = og / nx;
;             if (og + 1u == (tg + 1u) * nx) xb_add(&bar[XB_TOPGEN], 1u);
;             else XB_SPIN(xb_ld(&bar[XB_TOPGEN]) == tg, bar);
;             __builtin_amdgcn_fence(__ATOMIC_ACQUIRE, "agent");
;             xb_add(&bar[XB_XGEN(b.x)], 1u);
;             asm volatile("s_waitcnt vmcnt(0)" ::: "memory");
.LBB0_1169:
	s_or_b64 exec, exec, s[8:9]
	s_mov_b64 s[8:9], exec
	v_mbcnt_lo_u32_b32 v2, s8, 0
	v_mbcnt_hi_u32_b32 v2, s9, v2
	v_cmp_eq_u32_e32 vcc, 0, v2
	s_waitcnt vmcnt(0)
	buffer_inv sc1
	s_and_saveexec_b64 s[12:13], vcc
	s_cbranch_execz .LBB0_1171
	s_bcnt1_i32_b64 s3, s[8:9]
	v_mov_b32_e32 v2, 0x2000
	v_mov_b32_e32 v3, s3
.LBB0_1171:
	s_or_b64 exec, exec, s[12:13]
	s_waitcnt vmcnt(0)

; __device__ __forceinline__ unsigned xb_ld(unsigned* p)              { return __hip_atomic_load(p, __ATOMIC_RELAXED, __HIP_MEMORY_SCOPE_AGENT); }
; __device__ __forceinline__ unsigned xb_add(unsigned* p, unsigned v) { return __hip_atomic_fetch_add(p, v, __ATOMIC_RELAXED, __HIP_MEMORY_SCOPE_AGENT); }
; #define XB_SPIN(cond, bar) do { unsigned _sp = 0; while (cond) { __builtin_amdgcn_s_sleep(1); \
;     if ((++_sp & 255u) == 0u) { if (xb_ld(&(bar)[XB_TMO])) break; if (_sp > XB_SPIN_CAP) { atomicAdd(&(bar)[XB_TMO], 1u); break; } } } } while (0)
; __device__ __forceinline__ void xcd_barrier(const XcdBarrier& b) {
;     ...
;             const unsigned og = xb_add(&bar[XB_TOP], 1u);
;             const unsigned tg = og / nx;
;             if (og + 1u == (tg + 1u) * nx) xb_add(&bar[XB_TOPGEN], 1u);
;             else XB_SPIN(xb_ld(&bar[XB_TOPGEN]) == tg, bar);
;             __builtin_amdgcn_fence(__ATOMIC_ACQUIRE, "agent");
;             xb_add(&bar[XB_XGEN(b.x)], 1u);
;             asm volatile("s_waitcnt vmcnt(0)" ::: "memory");
.LBB0_1283:
	s_or_b64 exec, exec, s[8:9]
	s_mov_b64 s[8:9], exec
	v_mbcnt_lo_u32_b32 v2, s8, 0
	v_mbcnt_hi_u32_b32 v2, s9, v2
	v_cmp_eq_u32_e32 vcc, 0, v2
	s_waitcnt vmcnt(0)
	buffer_inv sc1
	s_and_saveexec_b64 s[12:13], vcc
	s_cbranch_execz .LBB0_1285
	s_bcnt1_i32_b64 s3, s[8:9]
	v_mov_b32_e32 v2, 0x2000
	v_mov_b32_e32 v3, s3
.LBB0_1285:
	s_or_b64 exec, exec, s[12:13]
	s_waitcnt vmcnt(0)

; __device__ __forceinline__ unsigned xb_ld(unsigned* p)              { return __hip_atomic_load(p, __ATOMIC_RELAXED, __HIP_MEMORY_SCOPE_AGENT); }
; __device__ __forceinline__ unsigned xb_add(unsigned* p, unsigned v) { return __hip_atomic_fetch_add(p, v, __ATOMIC_RELAXED, __HIP_MEMORY_SCOPE_AGENT); }
; #define XB_SPIN(cond, bar) do { unsigned _sp = 0; while (cond) { __builtin_amdgcn_s_sleep(1); \
;     if ((++_sp & 255u) == 0u) { if (xb_ld(&(bar)[XB_TMO])) break; if (_sp > XB_SPIN_CAP) { atomicAdd(&(bar)[XB_TMO], 1u); break; } } } } while (0)
; __device__ __forceinline__ void xcd_barrier(const XcdBarrier& b) {
;     ...
;             const unsigned og = xb_add(&bar[XB_TOP], 1u);
;             const unsigned tg = og / nx;
;             if (og + 1u == (tg + 1u) * nx) xb_add(&bar[XB_TOPGEN], 1u);
;             else XB_SPIN(xb_ld(&bar[XB_TOPGEN]) == tg, bar);
;             __builtin_amdgcn_fence(__ATOMIC_ACQUIRE, "agent");
;             xb_add(&bar[XB_XGEN(b.x)], 1u);
;             asm volatile("s_waitcnt vmcnt(0)" ::: "memory");
.LBB0_1382:
	s_or_b64 exec, exec, s[8:9]
	s_mov_b64 s[8:9], exec
	v_mbcnt_lo_u32_b32 v2, s8, 0
	v_mbcnt_hi_u32_b32 v2, s9, v2
	v_cmp_eq_u32_e32 vcc, 0, v2
	s_waitcnt vmcnt(0)
	buffer_inv sc1
	s_and_saveexec_b64 s[12:13], vcc
	s_cbranch_execz .LBB0_1384
	s_bcnt1_i32_b64 s3, s[8:9]
	v_mov_b32_e32 v2, 0x2000
	v_mov_b32_e32 v3, s3
.LBB0_1384:
	s_or_b64 exec, exec, s[12:13]
	s_waitcnt vmcnt(0)

; __device__ __forceinline__ unsigned xb_ld(unsigned* p)              { return __hip_atomic_load(p, __ATOMIC_RELAXED, __HIP_MEMORY_SCOPE_AGENT); }
; __device__ __forceinline__ unsigned xb_add(unsigned* p, unsigned v) { return __hip_atomic_fetch_add(p, v, __ATOMIC_RELAXED, __HIP_MEMORY_SCOPE_AGENT); }
; #define XB_SPIN(cond, bar) do { unsigned _sp = 0; while (cond) { __builtin_amdgcn_s_sleep(1); \
;     if ((++_sp & 255u) == 0u) { if (xb_ld(&(bar)[XB_TMO])) break; if (_sp > XB_SPIN_CAP) { atomicAdd(&(bar)[XB_TMO], 1u); break; } } } } while (0)
; __device__ __forceinline__ void xcd_barrier(const XcdBarrier& b) {
;     ...
;             const unsigned og = xb_add(&bar[XB_TOP], 1u);
;             const unsigned tg = og / nx;
;             if (og + 1u == (tg + 1u) * nx) xb_add(&bar[XB_TOPGEN], 1u);
;             else XB_SPIN(xb_ld(&bar[XB_TOPGEN]) == tg, bar);
;             __builtin_amdgcn_fence(__ATOMIC_ACQUIRE, "agent");
;             xb_add(&bar[XB_XGEN(b.x)], 1u);
;             asm volatile("s_waitcnt vmcnt(0)" ::: "memory");
.LBB0_1456:
	s_or_b64 exec, exec, s[20:21]
	s_mov_b64 s[20:21], exec
	v_mbcnt_lo_u32_b32 v2, s20, 0
	v_mbcnt_hi_u32_b32 v2, s21, v2
	v_cmp_eq_u32_e32 vcc, 0, v2
	s_waitcnt vmcnt(0)
	buffer_inv sc1
	s_and_saveexec_b64 s[22:23], vcc
	s_cbranch_execz .LBB0_1458
	s_bcnt1_i32_b64 s3, s[20:21]
	v_mov_b32_e32 v2, 0x2000
	v_mov_b32_e32 v3, s3
.LBB0_1458:
	s_or_b64 exec, exec, s[22:23]
	s_waitcnt vmcnt(0)

; __device__ __forceinline__ unsigned xb_ld(unsigned* p)              { return __hip_atomic_load(p, __ATOMIC_RELAXED, __HIP_MEMORY_SCOPE_AGENT); }
; __device__ __forceinline__ unsigned xb_add(unsigned* p, unsigned v) { return __hip_atomic_fetch_add(p, v, __ATOMIC_RELAXED, __HIP_MEMORY_SCOPE_AGENT); }
; #define XB_SPIN(cond, bar) do { unsigned _sp = 0; while (cond) { __builtin_amdgcn_s_sleep(1); \
;     if ((++_sp & 255u) == 0u) { if (xb_ld(&(bar)[XB_TMO])) break; if (_sp > XB_SPIN_CAP) { atomicAdd(&(bar)[XB_TMO], 1u); break; } } } } while (0)
; __device__ __forceinline__ void xcd_barrier(const XcdBarrier& b) {
;     ...
;             const unsigned og = xb_add(&bar[XB_TOP], 1u);
;             const unsigned tg = og / nx;
;             if (og + 1u == (tg + 1u) * nx) xb_add(&bar[XB_TOPGEN], 1u);
;             else XB_SPIN(xb_ld(&bar[XB_TOPGEN]) == tg, bar);
;             __builtin_amdgcn_fence(__ATOMIC_ACQUIRE, "agent");
;             xb_add(&bar[XB_XGEN(b.x)], 1u);
;             asm volatile("s_waitcnt vmcnt(0)" ::: "memory");
.LBB0_1535:
	s_or_b64 exec, exec, s[8:9]
	s_mov_b64 s[8:9], exec
	v_mbcnt_lo_u32_b32 v2, s8, 0
	v_mbcnt_hi_u32_b32 v2, s9, v2
	v_cmp_eq_u32_e32 vcc, 0, v2
	s_waitcnt vmcnt(0)
	buffer_inv sc1
	s_and_saveexec_b64 s[18:19], vcc
	s_cbranch_execz .LBB0_1537
	s_bcnt1_i32_b64 s3, s[8:9]
	v_mov_b32_e32 v2, 0x2000
	v_mov_b32_e32 v3, s3
.LBB0_1537:
	s_or_b64 exec, exec, s[18:19]
	s_waitcnt vmcnt(0)

; __device__ __forceinline__ unsigned xb_ld(unsigned* p)              { return __hip_atomic_load(p, __ATOMIC_RELAXED, __HIP_MEMORY_SCOPE_AGENT); }
; __device__ __forceinline__ unsigned xb_add(unsigned* p, unsigned v) { return __hip_atomic_fetch_add(p, v, __ATOMIC_RELAXED, __HIP_MEMORY_SCOPE_AGENT); }
; #define XB_SPIN(cond, bar) do { unsigned _sp = 0; while (cond) { __builtin_amdgcn_s_sleep(1); \
;     if ((++_sp & 255u) == 0u) { if (xb_ld(&(bar)[XB_TMO])) break; if (_sp > XB_SPIN_CAP) { atomicAdd(&(bar)[XB_TMO], 1u); break; } } } } while (0)
; __device__ __forceinline__ void xcd_barrier(const XcdBarrier& b) {
;     ...
;             const unsigned og = xb_add(&bar[XB_TOP], 1u);
;             const unsigned tg = og / nx;
;             if (og + 1u == (tg + 1u) * nx) xb_add(&bar[XB_TOPGEN], 1u);
;             else XB_SPIN(xb_ld(&bar[XB_TOPGEN]) == tg, bar);
;             __builtin_amdgcn_fence(__ATOMIC_ACQUIRE, "agent");
;             xb_add(&bar[XB_XGEN(b.x)], 1u);
;             asm volatile("s_waitcnt vmcnt(0)" ::: "memory");
.LBB0_1606:
	s_or_b64 exec, exec, s[20:21]
	s_mov_b64 s[20:21], exec
	v_mbcnt_lo_u32_b32 v2, s20, 0
	v_mbcnt_hi_u32_b32 v2, s21, v2
	v_cmp_eq_u32_e32 vcc, 0, v2
	s_waitcnt vmcnt(0)
	buffer_inv sc1
	s_and_saveexec_b64 s[22:23], vcc
	s_cbranch_execz .LBB0_1608
	s_bcnt1_i32_b64 s3, s[20:21]
	v_mov_b32_e32 v2, 0x2000
	v_mov_b32_e32 v3, s3
.LBB0_1608:
	s_or_b64 exec, exec, s[22:23]
	s_waitcnt vmcnt(0)

; __device__ __forceinline__ unsigned xb_ld(unsigned* p)              { return __hip_atomic_load(p, __ATOMIC_RELAXED, __HIP_MEMORY_SCOPE_AGENT); }
; __device__ __forceinline__ unsigned xb_add(unsigned* p, unsigned v) { return __hip_atomic_fetch_add(p, v, __ATOMIC_RELAXED, __HIP_MEMORY_SCOPE_AGENT); }
; #define XB_SPIN(cond, bar) do { unsigned _sp = 0; while (cond) { __builtin_amdgcn_s_sleep(1); \
;     if ((++_sp & 255u) == 0u) { if (xb_ld(&(bar)[XB_TMO])) break; if (_sp > XB_SPIN_CAP) { atomicAdd(&(bar)[XB_TMO], 1u); break; } } } } while (0)
; __device__ __forceinline__ void xcd_barrier(const XcdBarrier& b) {
;     ...
;             const unsigned og = xb_add(&bar[XB_TOP], 1u);
;             const unsigned tg = og / nx;
;             if (og + 1u == (tg + 1u) * nx) xb_add(&bar[XB_TOPGEN], 1u);
;             else XB_SPIN(xb_ld(&bar[XB_TOPGEN]) == tg, bar);
;             __builtin_amdgcn_fence(__ATOMIC_ACQUIRE, "agent");
;             xb_add(&bar[XB_XGEN(b.x)], 1u);
;             asm volatile("s_waitcnt vmcnt(0)" ::: "memory");
.LBB0_1707:
	s_or_b64 exec, exec, s[6:7]
	s_mov_b64 s[6:7], exec
	v_mbcnt_lo_u32_b32 v0, s6, 0
	v_mbcnt_hi_u32_b32 v0, s7, v0
	v_cmp_eq_u32_e32 vcc, 0, v0
	s_waitcnt vmcnt(0)
	buffer_inv sc1
	s_and_saveexec_b64 s[8:9], vcc
	s_cbranch_execz .LBB0_1709
	s_bcnt1_i32_b64 s6, s[6:7]
	v_mov_b32_e32 v0, 0x2000
	v_mov_b32_e32 v1, s6
.LBB0_1709:
	s_or_b64 exec, exec, s[8:9]
	s_waitcnt vmcnt(0)
